# grid barrier: waiting workgroups poll the cross-XCD release word directly (their XCD is quiescent and already invalidated); local release add removed
# speedup vs baseline: 1.0047x; 1.0047x over previous
; __device__ __forceinline__ unsigned xb_ld(unsigned* p)              { return __hip_atomic_load(p, __ATOMIC_RELAXED, __HIP_MEMORY_SCOPE_AGENT); }
; __device__ __forceinline__ unsigned xb_add(unsigned* p, unsigned v) { return __hip_atomic_fetch_add(p, v, __ATOMIC_RELAXED, __HIP_MEMORY_SCOPE_AGENT); }
; #define XB_SPIN(cond, bar) do { unsigned _sp = 0; while (cond) { __builtin_amdgcn_s_sleep(1); \
;     if ((++_sp & 255u) == 0u) { if (xb_ld(&(bar)[XB_TMO])) break; if (_sp > XB_SPIN_CAP) { atomicAdd(&(bar)[XB_TMO], 1u); break; } } } } while (0)
; __device__ __forceinline__ void xcd_barrier(const XcdBarrier& b, int wave_id) {
;     ...
;         const unsigned old = xb_add(&bar[XB_XSUB(b.x)], 1u);
;         const unsigned gen = old / nloc;
;         if (old + 1u == (gen + 1u) * nloc) {
;             __builtin_amdgcn_fence(__ATOMIC_RELEASE, "agent");
;             asm volatile("s_waitcnt vmcnt(0)" ::: "memory");
;             const unsigned og = xb_add(&bar[XB_TOP], 1u);
;             const unsigned tg = og / nx;
;             if (og + 1u == (tg + 1u) * nx) xb_add(&bar[XB_TOPGEN], 1u);
;             else XB_SPIN(xb_ld(&bar[XB_TOPGEN]) == tg, bar);
;             __builtin_amdgcn_fence(__ATOMIC_ACQUIRE, "agent");
;             xb_add(&bar[XB_XGEN(b.x)], 1u);
;             asm volatile("s_waitcnt vmcnt(0)" ::: "memory");
;         } else {
;             XB_SPIN(xb_ld(&bar[XB_XGEN(b.x)]) == gen, bar);
.LBB0_65:
	s_or_b64 exec, exec, s[18:19]
	v_cvt_f32_u32_e32 v4, v2
	s_waitcnt vmcnt(0)
	v_readfirstlane_b32 s8, v3
	v_sub_u32_e32 v3, 0, v2
	v_rcp_iflag_f32_e32 v4, v4
	v_add_u32_e32 v5, s8, v1
	v_mul_f32_e32 v4, 0x4f7ffffe, v4
	v_cvt_u32_f32_e32 v4, v4
	v_mul_lo_u32 v1, v3, v4
	v_mul_hi_u32 v1, v4, v1
	v_add_u32_e32 v1, v4, v1
	v_mul_hi_u32 v1, v5, v1
	v_mul_lo_u32 v3, v1, v2
	v_sub_u32_e32 v3, v5, v3
	v_add_u32_e32 v4, 1, v1
	v_cmp_ge_u32_e32 vcc, v3, v2
	s_nop 1
	v_cndmask_b32_e32 v1, v1, v4, vcc
	v_sub_u32_e32 v4, v3, v2
	v_cndmask_b32_e32 v3, v3, v4, vcc
	v_add_u32_e32 v4, 1, v1
	v_cmp_ge_u32_e32 vcc, v3, v2
	v_add_u32_e32 v3, 1, v5
	s_nop 0
	v_cndmask_b32_e32 v1, v1, v4, vcc
	v_mul_lo_u32 v4, v2, v1
	v_add_u32_e32 v2, v4, v2
	v_cmp_ne_u32_e32 vcc, v3, v2
	s_and_saveexec_b64 s[8:9], vcc
	s_xor_b64 s[8:9], exec, s[8:9]
	s_cbranch_execz .LBB0_79
	s_waitcnt lgkmcnt(0)
	buffer_inv sc1
	v_mov_b32_e32 v0, 0
	s_add_u32 s22, s14, 0xff43500
	s_addc_u32 s23, s15, 0
	global_load_dword v0, v0, s[22:23] sc1
	s_waitcnt vmcnt(0)
	v_cmp_eq_u32_e32 vcc, v0, v1
	s_and_saveexec_b64 s[18:19], vcc
	s_cbranch_execz .LBB0_78
	s_add_u32 s20, s14, 0xff40200
	s_addc_u32 s21, s15, 0
	s_mov_b32 s26, 1
	s_mov_b64 s[30:31], 0
	v_mov_b32_e32 v0, 0
	s_branch .LBB0_69

; __device__ __forceinline__ unsigned xb_add(unsigned* p, unsigned v) { return __hip_atomic_fetch_add(p, v, __ATOMIC_RELAXED, __HIP_MEMORY_SCOPE_AGENT); }
; __device__ __forceinline__ void xcd_barrier(const XcdBarrier& b, int wave_id) {
;     ...
;             __builtin_amdgcn_fence(__ATOMIC_ACQUIRE, "agent");
;             xb_add(&bar[XB_XGEN(b.x)], 1u);
;             asm volatile("s_waitcnt vmcnt(0)" ::: "memory");
.LBB0_96:
	s_or_b64 exec, exec, s[8:9]
	s_mov_b64 s[8:9], exec
	v_mbcnt_lo_u32_b32 v0, s8, 0
	v_mbcnt_hi_u32_b32 v0, s9, v0
	v_cmp_eq_u32_e32 vcc, 0, v0
	s_nop 0
	s_nop 0
	s_nop 0
	s_and_saveexec_b64 s[18:19], vcc
	s_cbranch_execz .LBB0_98
	s_bcnt1_i32_b64 s8, s[8:9]
	v_mov_b32_e32 v0, 0x2000
	v_mov_b32_e32 v1, s8
	s_nop 0

; __device__ __forceinline__ unsigned xb_ld(unsigned* p)              { return __hip_atomic_load(p, __ATOMIC_RELAXED, __HIP_MEMORY_SCOPE_AGENT); }
; __device__ __forceinline__ unsigned xb_add(unsigned* p, unsigned v) { return __hip_atomic_fetch_add(p, v, __ATOMIC_RELAXED, __HIP_MEMORY_SCOPE_AGENT); }
; #define XB_SPIN(cond, bar) do { unsigned _sp = 0; while (cond) { __builtin_amdgcn_s_sleep(1); \
;     if ((++_sp & 255u) == 0u) { if (xb_ld(&(bar)[XB_TMO])) break; if (_sp > XB_SPIN_CAP) { atomicAdd(&(bar)[XB_TMO], 1u); break; } } } } while (0)
; __device__ __forceinline__ void xcd_barrier(const XcdBarrier& b, int wave_id) {
;     ...
;         const unsigned old = xb_add(&bar[XB_XSUB(b.x)], 1u);
;         const unsigned gen = old / nloc;
;         if (old + 1u == (gen + 1u) * nloc) {
;             __builtin_amdgcn_fence(__ATOMIC_RELEASE, "agent");
;             asm volatile("s_waitcnt vmcnt(0)" ::: "memory");
;             const unsigned og = xb_add(&bar[XB_TOP], 1u);
;             const unsigned tg = og / nx;
;             if (og + 1u == (tg + 1u) * nx) xb_add(&bar[XB_TOPGEN], 1u);
;             else XB_SPIN(xb_ld(&bar[XB_TOPGEN]) == tg, bar);
;             __builtin_amdgcn_fence(__ATOMIC_ACQUIRE, "agent");
;             xb_add(&bar[XB_XGEN(b.x)], 1u);
;             asm volatile("s_waitcnt vmcnt(0)" ::: "memory");
;         } else {
;             XB_SPIN(xb_ld(&bar[XB_XGEN(b.x)]) == gen, bar);
.LBB0_225:
	s_or_b64 exec, exec, s[10:11]
	v_cvt_f32_u32_e32 v4, v2
	s_waitcnt vmcnt(0)
	v_readfirstlane_b32 s8, v3
	v_sub_u32_e32 v3, 0, v2
	v_rcp_iflag_f32_e32 v4, v4
	v_add_u32_e32 v5, s8, v1
	v_mul_f32_e32 v4, 0x4f7ffffe, v4
	v_cvt_u32_f32_e32 v4, v4
	v_mul_lo_u32 v1, v3, v4
	v_mul_hi_u32 v1, v4, v1
	v_add_u32_e32 v1, v4, v1
	v_mul_hi_u32 v1, v5, v1
	v_mul_lo_u32 v3, v1, v2
	v_sub_u32_e32 v3, v5, v3
	v_add_u32_e32 v4, 1, v1
	v_cmp_ge_u32_e32 vcc, v3, v2
	s_nop 1
	v_cndmask_b32_e32 v1, v1, v4, vcc
	v_sub_u32_e32 v4, v3, v2
	v_cndmask_b32_e32 v3, v3, v4, vcc
	v_add_u32_e32 v4, 1, v1
	v_cmp_ge_u32_e32 vcc, v3, v2
	v_add_u32_e32 v3, 1, v5
	s_nop 0
	v_cndmask_b32_e32 v1, v1, v4, vcc
	v_mul_lo_u32 v4, v2, v1
	v_add_u32_e32 v2, v4, v2
	v_cmp_ne_u32_e32 vcc, v3, v2
	s_and_saveexec_b64 s[8:9], vcc
	s_xor_b64 s[8:9], exec, s[8:9]
	s_cbranch_execz .LBB0_239
	s_waitcnt lgkmcnt(0)
	buffer_inv sc1
	v_mov_b32_e32 v0, 0
	s_add_u32 s22, s14, 0xff43500
	s_addc_u32 s23, s15, 0
	global_load_dword v0, v0, s[22:23] sc1
	s_waitcnt vmcnt(0)
	v_cmp_eq_u32_e32 vcc, v0, v1
	s_and_saveexec_b64 s[10:11], vcc
	s_cbranch_execz .LBB0_238
	s_add_u32 s20, s14, 0xff40200
	s_addc_u32 s21, s15, 0
	s_mov_b32 s26, 1
	s_mov_b64 s[44:45], 0
	v_mov_b32_e32 v0, 0
	s_branch .LBB0_229

; __device__ __forceinline__ unsigned xb_add(unsigned* p, unsigned v) { return __hip_atomic_fetch_add(p, v, __ATOMIC_RELAXED, __HIP_MEMORY_SCOPE_AGENT); }
; __device__ __forceinline__ void xcd_barrier(const XcdBarrier& b, int wave_id) {
;     ...
;             __builtin_amdgcn_fence(__ATOMIC_ACQUIRE, "agent");
;             xb_add(&bar[XB_XGEN(b.x)], 1u);
;             asm volatile("s_waitcnt vmcnt(0)" ::: "memory");
.LBB0_256:
	s_or_b64 exec, exec, s[8:9]
	s_mov_b64 s[8:9], exec
	v_mbcnt_lo_u32_b32 v0, s8, 0
	v_mbcnt_hi_u32_b32 v0, s9, v0
	v_cmp_eq_u32_e32 vcc, 0, v0
	s_nop 0
	s_nop 0
	s_nop 0
	s_and_saveexec_b64 s[10:11], vcc
	s_cbranch_execz .LBB0_258
	s_bcnt1_i32_b64 s8, s[8:9]
	v_mov_b32_e32 v0, 0x2000
	v_mov_b32_e32 v1, s8
	s_nop 0

; __device__ __forceinline__ unsigned xb_ld(unsigned* p)              { return __hip_atomic_load(p, __ATOMIC_RELAXED, __HIP_MEMORY_SCOPE_AGENT); }
; __device__ __forceinline__ unsigned xb_add(unsigned* p, unsigned v) { return __hip_atomic_fetch_add(p, v, __ATOMIC_RELAXED, __HIP_MEMORY_SCOPE_AGENT); }
; #define XB_SPIN(cond, bar) do { unsigned _sp = 0; while (cond) { __builtin_amdgcn_s_sleep(1); \
;     if ((++_sp & 255u) == 0u) { if (xb_ld(&(bar)[XB_TMO])) break; if (_sp > XB_SPIN_CAP) { atomicAdd(&(bar)[XB_TMO], 1u); break; } } } } while (0)
; __device__ __forceinline__ void xcd_barrier(const XcdBarrier& b, int wave_id) {
;     ...
;         const unsigned old = xb_add(&bar[XB_XSUB(b.x)], 1u);
;         const unsigned gen = old / nloc;
;         if (old + 1u == (gen + 1u) * nloc) {
;             __builtin_amdgcn_fence(__ATOMIC_RELEASE, "agent");
;             asm volatile("s_waitcnt vmcnt(0)" ::: "memory");
;             const unsigned og = xb_add(&bar[XB_TOP], 1u);
;             const unsigned tg = og / nx;
;             if (og + 1u == (tg + 1u) * nx) xb_add(&bar[XB_TOPGEN], 1u);
;             else XB_SPIN(xb_ld(&bar[XB_TOPGEN]) == tg, bar);
;             __builtin_amdgcn_fence(__ATOMIC_ACQUIRE, "agent");
;             xb_add(&bar[XB_XGEN(b.x)], 1u);
;             asm volatile("s_waitcnt vmcnt(0)" ::: "memory");
;         } else {
;             XB_SPIN(xb_ld(&bar[XB_XGEN(b.x)]) == gen, bar);
.LBB0_387:
	s_or_b64 exec, exec, s[22:23]
	v_cvt_f32_u32_e32 v4, v2
	s_waitcnt vmcnt(0)
	v_readfirstlane_b32 s6, v3
	v_sub_u32_e32 v3, 0, v2
	v_rcp_iflag_f32_e32 v4, v4
	v_add_u32_e32 v5, s6, v1
	v_mul_f32_e32 v4, 0x4f7ffffe, v4
	v_cvt_u32_f32_e32 v4, v4
	v_mul_lo_u32 v1, v3, v4
	v_mul_hi_u32 v1, v4, v1
	v_add_u32_e32 v1, v4, v1
	v_mul_hi_u32 v1, v5, v1
	v_mul_lo_u32 v3, v1, v2
	v_sub_u32_e32 v3, v5, v3
	v_add_u32_e32 v4, 1, v1
	v_cmp_ge_u32_e32 vcc, v3, v2
	s_nop 1
	v_cndmask_b32_e32 v1, v1, v4, vcc
	v_sub_u32_e32 v4, v3, v2
	v_cndmask_b32_e32 v3, v3, v4, vcc
	v_add_u32_e32 v4, 1, v1
	v_cmp_ge_u32_e32 vcc, v3, v2
	v_add_u32_e32 v3, 1, v5
	s_nop 0
	v_cndmask_b32_e32 v1, v1, v4, vcc
	v_mul_lo_u32 v4, v2, v1
	v_add_u32_e32 v2, v4, v2
	v_cmp_ne_u32_e32 vcc, v3, v2
	s_and_saveexec_b64 s[6:7], vcc
	s_xor_b64 s[20:21], exec, s[6:7]
	s_cbranch_execz .LBB0_401
	s_waitcnt lgkmcnt(0)
	buffer_inv sc1
	v_mov_b32_e32 v0, 0
	s_add_u32 s44, s14, 0xff43500
	s_addc_u32 s45, s15, 0
	global_load_dword v0, v0, s[44:45] sc1
	s_waitcnt vmcnt(0)
	v_cmp_eq_u32_e32 vcc, v0, v1
	s_and_saveexec_b64 s[22:23], vcc
	s_cbranch_execz .LBB0_400
	s_add_u32 s42, s14, 0xff40200
	s_addc_u32 s43, s15, 0
	s_mov_b32 s6, 1
	s_mov_b64 s[46:47], 0
	v_mov_b32_e32 v0, 0
	s_branch .LBB0_391

; __device__ __forceinline__ unsigned xb_add(unsigned* p, unsigned v) { return __hip_atomic_fetch_add(p, v, __ATOMIC_RELAXED, __HIP_MEMORY_SCOPE_AGENT); }
; __device__ __forceinline__ void xcd_barrier(const XcdBarrier& b, int wave_id) {
;     ...
;             __builtin_amdgcn_fence(__ATOMIC_ACQUIRE, "agent");
;             xb_add(&bar[XB_XGEN(b.x)], 1u);
;             asm volatile("s_waitcnt vmcnt(0)" ::: "memory");
.LBB0_418:
	s_or_b64 exec, exec, s[20:21]
	s_mov_b64 s[20:21], exec
	v_mbcnt_lo_u32_b32 v0, s20, 0
	v_mbcnt_hi_u32_b32 v0, s21, v0
	v_cmp_eq_u32_e32 vcc, 0, v0
	s_nop 0
	s_nop 0
	s_nop 0
	s_and_saveexec_b64 s[22:23], vcc
	s_cbranch_execz .LBB0_420
	s_bcnt1_i32_b64 s6, s[20:21]
	v_mov_b32_e32 v0, 0x2000
	v_mov_b32_e32 v1, s6
	s_nop 0

; __device__ __forceinline__ unsigned xb_ld(unsigned* p)              { return __hip_atomic_load(p, __ATOMIC_RELAXED, __HIP_MEMORY_SCOPE_AGENT); }
; __device__ __forceinline__ unsigned xb_add(unsigned* p, unsigned v) { return __hip_atomic_fetch_add(p, v, __ATOMIC_RELAXED, __HIP_MEMORY_SCOPE_AGENT); }
; #define XB_SPIN(cond, bar) do { unsigned _sp = 0; while (cond) { __builtin_amdgcn_s_sleep(1); \
;     if ((++_sp & 255u) == 0u) { if (xb_ld(&(bar)[XB_TMO])) break; if (_sp > XB_SPIN_CAP) { atomicAdd(&(bar)[XB_TMO], 1u); break; } } } } while (0)
; __device__ __forceinline__ void xcd_barrier(const XcdBarrier& b, int wave_id) {
;     ...
;         const unsigned old = xb_add(&bar[XB_XSUB(b.x)], 1u);
;         const unsigned gen = old / nloc;
;         if (old + 1u == (gen + 1u) * nloc) {
;             __builtin_amdgcn_fence(__ATOMIC_RELEASE, "agent");
;             asm volatile("s_waitcnt vmcnt(0)" ::: "memory");
;             const unsigned og = xb_add(&bar[XB_TOP], 1u);
;             const unsigned tg = og / nx;
;             if (og + 1u == (tg + 1u) * nx) xb_add(&bar[XB_TOPGEN], 1u);
;             else XB_SPIN(xb_ld(&bar[XB_TOPGEN]) == tg, bar);
;             __builtin_amdgcn_fence(__ATOMIC_ACQUIRE, "agent");
;             xb_add(&bar[XB_XGEN(b.x)], 1u);
;             asm volatile("s_waitcnt vmcnt(0)" ::: "memory");
;         } else {
;             XB_SPIN(xb_ld(&bar[XB_XGEN(b.x)]) == gen, bar);
.LBB0_470:
	s_or_b64 exec, exec, s[22:23]
	v_cvt_f32_u32_e32 v4, v2
	s_waitcnt vmcnt(0)
	v_readfirstlane_b32 s6, v3
	v_sub_u32_e32 v3, 0, v2
	v_rcp_iflag_f32_e32 v4, v4
	v_add_u32_e32 v5, s6, v1
	v_mul_f32_e32 v4, 0x4f7ffffe, v4
	v_cvt_u32_f32_e32 v4, v4
	v_mul_lo_u32 v1, v3, v4
	v_mul_hi_u32 v1, v4, v1
	v_add_u32_e32 v1, v4, v1
	v_mul_hi_u32 v1, v5, v1
	v_mul_lo_u32 v3, v1, v2
	v_sub_u32_e32 v3, v5, v3
	v_add_u32_e32 v4, 1, v1
	v_cmp_ge_u32_e32 vcc, v3, v2
	s_nop 1
	v_cndmask_b32_e32 v1, v1, v4, vcc
	v_sub_u32_e32 v4, v3, v2
	v_cndmask_b32_e32 v3, v3, v4, vcc
	v_add_u32_e32 v4, 1, v1
	v_cmp_ge_u32_e32 vcc, v3, v2
	v_add_u32_e32 v3, 1, v5
	s_nop 0
	v_cndmask_b32_e32 v1, v1, v4, vcc
	v_mul_lo_u32 v4, v2, v1
	v_add_u32_e32 v2, v4, v2
	v_cmp_ne_u32_e32 vcc, v3, v2
	s_and_saveexec_b64 s[6:7], vcc
	s_xor_b64 s[10:11], exec, s[6:7]
	s_cbranch_execz .LBB0_484
	s_waitcnt lgkmcnt(0)
	buffer_inv sc1
	v_mov_b32_e32 v0, 0
	s_add_u32 s40, s14, 0xff43500
	s_addc_u32 s41, s15, 0
	global_load_dword v0, v0, s[40:41] sc1
	s_waitcnt vmcnt(0)
	v_cmp_eq_u32_e32 vcc, v0, v1
	s_and_saveexec_b64 s[22:23], vcc
	s_cbranch_execz .LBB0_483
	s_add_u32 s38, s14, 0xff40200
	s_addc_u32 s39, s15, 0
	s_mov_b32 s6, 1
	s_mov_b64 s[42:43], 0
	v_mov_b32_e32 v0, 0
	s_branch .LBB0_474

; __device__ __forceinline__ unsigned xb_add(unsigned* p, unsigned v) { return __hip_atomic_fetch_add(p, v, __ATOMIC_RELAXED, __HIP_MEMORY_SCOPE_AGENT); }
; __device__ __forceinline__ void xcd_barrier(const XcdBarrier& b, int wave_id) {
;     ...
;             __builtin_amdgcn_fence(__ATOMIC_ACQUIRE, "agent");
;             xb_add(&bar[XB_XGEN(b.x)], 1u);
;             asm volatile("s_waitcnt vmcnt(0)" ::: "memory");
.LBB0_501:
	s_or_b64 exec, exec, s[10:11]
	s_mov_b64 s[10:11], exec
	v_mbcnt_lo_u32_b32 v0, s10, 0
	v_mbcnt_hi_u32_b32 v0, s11, v0
	v_cmp_eq_u32_e32 vcc, 0, v0
	s_nop 0
	s_nop 0
	s_nop 0
	s_and_saveexec_b64 s[22:23], vcc
	s_cbranch_execz .LBB0_503
	s_bcnt1_i32_b64 s6, s[10:11]
	v_mov_b32_e32 v0, 0x2000
	v_mov_b32_e32 v1, s6
	s_nop 0

; __device__ __forceinline__ unsigned xb_ld(unsigned* p)              { return __hip_atomic_load(p, __ATOMIC_RELAXED, __HIP_MEMORY_SCOPE_AGENT); }
; __device__ __forceinline__ unsigned xb_add(unsigned* p, unsigned v) { return __hip_atomic_fetch_add(p, v, __ATOMIC_RELAXED, __HIP_MEMORY_SCOPE_AGENT); }
; #define XB_SPIN(cond, bar) do { unsigned _sp = 0; while (cond) { __builtin_amdgcn_s_sleep(1); \
;     if ((++_sp & 255u) == 0u) { if (xb_ld(&(bar)[XB_TMO])) break; if (_sp > XB_SPIN_CAP) { atomicAdd(&(bar)[XB_TMO], 1u); break; } } } } while (0)
; __device__ __forceinline__ void xcd_barrier(const XcdBarrier& b, int wave_id) {
;     ...
;         const unsigned old = xb_add(&bar[XB_XSUB(b.x)], 1u);
;         const unsigned gen = old / nloc;
;         if (old + 1u == (gen + 1u) * nloc) {
;             __builtin_amdgcn_fence(__ATOMIC_RELEASE, "agent");
;             asm volatile("s_waitcnt vmcnt(0)" ::: "memory");
;             const unsigned og = xb_add(&bar[XB_TOP], 1u);
;             const unsigned tg = og / nx;
;             if (og + 1u == (tg + 1u) * nx) xb_add(&bar[XB_TOPGEN], 1u);
;             else XB_SPIN(xb_ld(&bar[XB_TOPGEN]) == tg, bar);
;             __builtin_amdgcn_fence(__ATOMIC_ACQUIRE, "agent");
;             xb_add(&bar[XB_XGEN(b.x)], 1u);
;             asm volatile("s_waitcnt vmcnt(0)" ::: "memory");
;         } else {
;             XB_SPIN(xb_ld(&bar[XB_XGEN(b.x)]) == gen, bar);
.LBB0_578:
	s_or_b64 exec, exec, s[22:23]
	v_cvt_f32_u32_e32 v4, v2
	s_waitcnt vmcnt(0)
	v_readfirstlane_b32 s8, v3
	v_sub_u32_e32 v3, 0, v2
	v_rcp_iflag_f32_e32 v4, v4
	v_add_u32_e32 v5, s8, v1
	v_mul_f32_e32 v4, 0x4f7ffffe, v4
	v_cvt_u32_f32_e32 v4, v4
	v_mul_lo_u32 v1, v3, v4
	v_mul_hi_u32 v1, v4, v1
	v_add_u32_e32 v1, v4, v1
	v_mul_hi_u32 v1, v5, v1
	v_mul_lo_u32 v3, v1, v2
	v_sub_u32_e32 v3, v5, v3
	v_add_u32_e32 v4, 1, v1
	v_cmp_ge_u32_e32 vcc, v3, v2
	s_nop 1
	v_cndmask_b32_e32 v1, v1, v4, vcc
	v_sub_u32_e32 v4, v3, v2
	v_cndmask_b32_e32 v3, v3, v4, vcc
	v_add_u32_e32 v4, 1, v1
	v_cmp_ge_u32_e32 vcc, v3, v2
	v_add_u32_e32 v3, 1, v5
	s_nop 0
	v_cndmask_b32_e32 v1, v1, v4, vcc
	v_mul_lo_u32 v4, v2, v1
	v_add_u32_e32 v2, v4, v2
	v_cmp_ne_u32_e32 vcc, v3, v2
	s_and_saveexec_b64 s[8:9], vcc
	s_xor_b64 s[8:9], exec, s[8:9]
	s_cbranch_execz .LBB0_592
	s_waitcnt lgkmcnt(0)
	buffer_inv sc1
	v_mov_b32_e32 v0, 0
	s_add_u32 s40, s14, 0xff43500
	s_addc_u32 s41, s15, 0
	global_load_dword v0, v0, s[40:41] sc1
	s_waitcnt vmcnt(0)
	v_cmp_eq_u32_e32 vcc, v0, v1
	s_and_saveexec_b64 s[22:23], vcc
	s_cbranch_execz .LBB0_591
	s_add_u32 s38, s14, 0xff40200
	s_addc_u32 s39, s15, 0
	s_mov_b32 s26, 1
	s_mov_b64 s[42:43], 0
	v_mov_b32_e32 v0, 0
	s_branch .LBB0_582

; __device__ __forceinline__ unsigned xb_add(unsigned* p, unsigned v) { return __hip_atomic_fetch_add(p, v, __ATOMIC_RELAXED, __HIP_MEMORY_SCOPE_AGENT); }
; __device__ __forceinline__ void xcd_barrier(const XcdBarrier& b, int wave_id) {
;     ...
;             __builtin_amdgcn_fence(__ATOMIC_ACQUIRE, "agent");
;             xb_add(&bar[XB_XGEN(b.x)], 1u);
;             asm volatile("s_waitcnt vmcnt(0)" ::: "memory");
.LBB0_609:
	s_or_b64 exec, exec, s[8:9]
	s_mov_b64 s[8:9], exec
	v_mbcnt_lo_u32_b32 v0, s8, 0
	v_mbcnt_hi_u32_b32 v0, s9, v0
	v_cmp_eq_u32_e32 vcc, 0, v0
	s_nop 0
	s_nop 0
	s_nop 0
	s_and_saveexec_b64 s[22:23], vcc
	s_cbranch_execz .LBB0_611
	s_bcnt1_i32_b64 s8, s[8:9]
	v_mov_b32_e32 v0, 0x2000
	v_mov_b32_e32 v1, s8
	s_nop 0

; __device__ __forceinline__ unsigned xb_ld(unsigned* p)              { return __hip_atomic_load(p, __ATOMIC_RELAXED, __HIP_MEMORY_SCOPE_AGENT); }
; __device__ __forceinline__ unsigned xb_add(unsigned* p, unsigned v) { return __hip_atomic_fetch_add(p, v, __ATOMIC_RELAXED, __HIP_MEMORY_SCOPE_AGENT); }
; #define XB_SPIN(cond, bar) do { unsigned _sp = 0; while (cond) { __builtin_amdgcn_s_sleep(1); \
;     if ((++_sp & 255u) == 0u) { if (xb_ld(&(bar)[XB_TMO])) break; if (_sp > XB_SPIN_CAP) { atomicAdd(&(bar)[XB_TMO], 1u); break; } } } } while (0)
; __device__ __forceinline__ void xcd_barrier(const XcdBarrier& b, int wave_id) {
;     ...
;         const unsigned old = xb_add(&bar[XB_XSUB(b.x)], 1u);
;         const unsigned gen = old / nloc;
;         if (old + 1u == (gen + 1u) * nloc) {
;             __builtin_amdgcn_fence(__ATOMIC_RELEASE, "agent");
;             asm volatile("s_waitcnt vmcnt(0)" ::: "memory");
;             const unsigned og = xb_add(&bar[XB_TOP], 1u);
;             const unsigned tg = og / nx;
;             if (og + 1u == (tg + 1u) * nx) xb_add(&bar[XB_TOPGEN], 1u);
;             else XB_SPIN(xb_ld(&bar[XB_TOPGEN]) == tg, bar);
;             __builtin_amdgcn_fence(__ATOMIC_ACQUIRE, "agent");
;             xb_add(&bar[XB_XGEN(b.x)], 1u);
;             asm volatile("s_waitcnt vmcnt(0)" ::: "memory");
;         } else {
;             XB_SPIN(xb_ld(&bar[XB_XGEN(b.x)]) == gen, bar);
.LBB0_674:
	s_or_b64 exec, exec, s[16:17]
	v_cvt_f32_u32_e32 v4, v2
	s_waitcnt vmcnt(0)
	v_readfirstlane_b32 s8, v3
	v_sub_u32_e32 v3, 0, v2
	v_rcp_iflag_f32_e32 v4, v4
	v_add_u32_e32 v5, s8, v1
	v_mul_f32_e32 v4, 0x4f7ffffe, v4
	v_cvt_u32_f32_e32 v4, v4
	v_mul_lo_u32 v1, v3, v4
	v_mul_hi_u32 v1, v4, v1
	v_add_u32_e32 v1, v4, v1
	v_mul_hi_u32 v1, v5, v1
	v_mul_lo_u32 v3, v1, v2
	v_sub_u32_e32 v3, v5, v3
	v_add_u32_e32 v4, 1, v1
	v_cmp_ge_u32_e32 vcc, v3, v2
	s_nop 1
	v_cndmask_b32_e32 v1, v1, v4, vcc
	v_sub_u32_e32 v4, v3, v2
	v_cndmask_b32_e32 v3, v3, v4, vcc
	v_add_u32_e32 v4, 1, v1
	v_cmp_ge_u32_e32 vcc, v3, v2
	v_add_u32_e32 v3, 1, v5
	s_nop 0
	v_cndmask_b32_e32 v1, v1, v4, vcc
	v_mul_lo_u32 v4, v2, v1
	v_add_u32_e32 v2, v4, v2
	v_cmp_ne_u32_e32 vcc, v3, v2
	s_and_saveexec_b64 s[8:9], vcc
	s_xor_b64 s[8:9], exec, s[8:9]
	s_cbranch_execz .LBB0_688
	s_waitcnt lgkmcnt(0)
	buffer_inv sc1
	v_mov_b32_e32 v0, 0
	s_add_u32 s22, s14, 0xff43500
	s_addc_u32 s23, s15, 0
	global_load_dword v0, v0, s[22:23] sc1
	s_waitcnt vmcnt(0)
	v_cmp_eq_u32_e32 vcc, v0, v1
	s_and_saveexec_b64 s[16:17], vcc
	s_cbranch_execz .LBB0_687
	s_add_u32 s20, s14, 0xff40200
	s_addc_u32 s21, s15, 0
	s_mov_b32 s26, 1
	s_mov_b64 s[36:37], 0
	v_mov_b32_e32 v0, 0
	s_branch .LBB0_678

; __device__ __forceinline__ unsigned xb_add(unsigned* p, unsigned v) { return __hip_atomic_fetch_add(p, v, __ATOMIC_RELAXED, __HIP_MEMORY_SCOPE_AGENT); }
; __device__ __forceinline__ void xcd_barrier(const XcdBarrier& b, int wave_id) {
;     ...
;             __builtin_amdgcn_fence(__ATOMIC_ACQUIRE, "agent");
;             xb_add(&bar[XB_XGEN(b.x)], 1u);
;             asm volatile("s_waitcnt vmcnt(0)" ::: "memory");
.LBB0_705:
	s_or_b64 exec, exec, s[8:9]
	s_mov_b64 s[8:9], exec
	v_mbcnt_lo_u32_b32 v0, s8, 0
	v_mbcnt_hi_u32_b32 v0, s9, v0
	v_cmp_eq_u32_e32 vcc, 0, v0
	s_nop 0
	s_nop 0
	s_nop 0
	s_and_saveexec_b64 s[16:17], vcc
	s_cbranch_execz .LBB0_707
	s_bcnt1_i32_b64 s8, s[8:9]
	v_mov_b32_e32 v0, 0x2000
	v_mov_b32_e32 v1, s8
	s_nop 0

; __device__ __forceinline__ unsigned xb_ld(unsigned* p)              { return __hip_atomic_load(p, __ATOMIC_RELAXED, __HIP_MEMORY_SCOPE_AGENT); }
; __device__ __forceinline__ unsigned xb_add(unsigned* p, unsigned v) { return __hip_atomic_fetch_add(p, v, __ATOMIC_RELAXED, __HIP_MEMORY_SCOPE_AGENT); }
; #define XB_SPIN(cond, bar) do { unsigned _sp = 0; while (cond) { __builtin_amdgcn_s_sleep(1); \
;     if ((++_sp & 255u) == 0u) { if (xb_ld(&(bar)[XB_TMO])) break; if (_sp > XB_SPIN_CAP) { atomicAdd(&(bar)[XB_TMO], 1u); break; } } } } while (0)
; __device__ __forceinline__ void xcd_barrier(const XcdBarrier& b, int wave_id) {
;     ...
;         const unsigned old = xb_add(&bar[XB_XSUB(b.x)], 1u);
;         const unsigned gen = old / nloc;
;         if (old + 1u == (gen + 1u) * nloc) {
;             __builtin_amdgcn_fence(__ATOMIC_RELEASE, "agent");
;             asm volatile("s_waitcnt vmcnt(0)" ::: "memory");
;             const unsigned og = xb_add(&bar[XB_TOP], 1u);
;             const unsigned tg = og / nx;
;             if (og + 1u == (tg + 1u) * nx) xb_add(&bar[XB_TOPGEN], 1u);
;             else XB_SPIN(xb_ld(&bar[XB_TOPGEN]) == tg, bar);
;             __builtin_amdgcn_fence(__ATOMIC_ACQUIRE, "agent");
;             xb_add(&bar[XB_XGEN(b.x)], 1u);
;             asm volatile("s_waitcnt vmcnt(0)" ::: "memory");
;         } else {
;             XB_SPIN(xb_ld(&bar[XB_XGEN(b.x)]) == gen, bar);
.LBB0_750:
	s_or_b64 exec, exec, s[18:19]
	v_cvt_f32_u32_e32 v4, v2
	s_waitcnt vmcnt(0)
	v_readfirstlane_b32 s3, v3
	v_sub_u32_e32 v3, 0, v2
	v_rcp_iflag_f32_e32 v4, v4
	v_add_u32_e32 v5, s3, v1
	v_mul_f32_e32 v4, 0x4f7ffffe, v4
	v_cvt_u32_f32_e32 v4, v4
	v_mul_lo_u32 v1, v3, v4
	v_mul_hi_u32 v1, v4, v1
	v_add_u32_e32 v1, v4, v1
	v_mul_hi_u32 v1, v5, v1
	v_mul_lo_u32 v3, v1, v2
	v_sub_u32_e32 v3, v5, v3
	v_add_u32_e32 v4, 1, v1
	v_cmp_ge_u32_e32 vcc, v3, v2
	s_nop 1
	v_cndmask_b32_e32 v1, v1, v4, vcc
	v_sub_u32_e32 v4, v3, v2
	v_cndmask_b32_e32 v3, v3, v4, vcc
	v_add_u32_e32 v4, 1, v1
	v_cmp_ge_u32_e32 vcc, v3, v2
	v_add_u32_e32 v3, 1, v5
	s_nop 0
	v_cndmask_b32_e32 v1, v1, v4, vcc
	v_mul_lo_u32 v4, v2, v1
	v_add_u32_e32 v2, v4, v2
	v_cmp_ne_u32_e32 vcc, v3, v2
	s_and_saveexec_b64 s[16:17], vcc
	s_xor_b64 s[16:17], exec, s[16:17]
	s_cbranch_execz .LBB0_764
	s_waitcnt lgkmcnt(0)
	buffer_inv sc1
	v_mov_b32_e32 v0, 0
	s_add_u32 s22, s14, 0xff43500
	s_addc_u32 s23, s15, 0
	global_load_dword v0, v0, s[22:23] sc1
	s_waitcnt vmcnt(0)
	v_cmp_eq_u32_e32 vcc, v0, v1
	s_and_saveexec_b64 s[18:19], vcc
	s_cbranch_execz .LBB0_763
	s_add_u32 s20, s14, 0xff40200
	s_addc_u32 s21, s15, 0
	s_mov_b32 s3, 1
	s_mov_b64 s[26:27], 0
	v_mov_b32_e32 v0, 0
	s_branch .LBB0_754

; __device__ __forceinline__ unsigned xb_add(unsigned* p, unsigned v) { return __hip_atomic_fetch_add(p, v, __ATOMIC_RELAXED, __HIP_MEMORY_SCOPE_AGENT); }
; __device__ __forceinline__ void xcd_barrier(const XcdBarrier& b, int wave_id) {
;     ...
;             __builtin_amdgcn_fence(__ATOMIC_ACQUIRE, "agent");
;             xb_add(&bar[XB_XGEN(b.x)], 1u);
;             asm volatile("s_waitcnt vmcnt(0)" ::: "memory");
.LBB0_781:
	s_or_b64 exec, exec, s[14:15]
	s_mov_b64 s[14:15], exec
	v_mbcnt_lo_u32_b32 v0, s14, 0
	v_mbcnt_hi_u32_b32 v0, s15, v0
	v_cmp_eq_u32_e32 vcc, 0, v0
	s_nop 0
	s_nop 0
	s_nop 0
	s_and_saveexec_b64 s[16:17], vcc
	s_cbranch_execz .LBB0_783
	s_bcnt1_i32_b64 s3, s[14:15]
	v_mov_b32_e32 v0, 0x2000
	v_mov_b32_e32 v1, s3
	s_nop 0
